# past: Q-row waits no longer wait for the previous group's partial stores; no Q prefetch in a wave's last group; prologue guards dropped
# speedup vs baseline: 1.0077x; 1.0077x over previous
.LBB0_254:
	s_and_b32 s0, s34, 11
	s_cmp_lg_u32 s0, 0
	s_cselect_b64 s[16:17], -1, 0
	s_cmp_lg_u32 s0, 3
	s_cselect_b64 s[18:19], -1, 0
	s_and_b64 s[16:17], s[16:17], s[18:19]
	s_cmp_lg_u32 s34, 8
	s_cselect_b64 s[18:19], -1, 0
	s_and_b64 s[16:17], s[18:19], s[16:17]
	s_add_i32 s0, s34, -13
	s_cmp_lt_u32 s0, -2
	s_cselect_b64 s[18:19], -1, 0
	s_and_b64 s[16:17], s[18:19], s[16:17]
	s_waitcnt vmcnt(10)
	v_cndmask_b32_e64 v0, 0, 1, s[16:17]
	v_cmp_ne_u32_e32 vcc, v0, v177
	s_cbranch_vccnz .LBB0_253
	s_lshl_b32 s0, s34, 15
	v_lshl_add_u64 v[24:25], v[152:153], 0, s[0:1]
	s_lshl_b32 s0, s34, 9
	v_mov_b32_e32 v133, v117
	v_lshl_add_u64 v[28:29], v[154:155], 0, s[0:1]
	v_lshl_add_u64 v[0:1], v[24:25], 0, v[132:133]
	v_mov_b32_e32 v135, v117
	s_barrier
	global_load_dwordx4 v[0:3], v[0:1], off
	v_lshl_add_u64 v[4:5], v[28:29], 0, v[134:135]
	v_mov_b32_e32 v137, v117
	global_load_dwordx4 v[4:7], v[4:5], off
	v_lshl_add_u64 v[8:9], v[24:25], 0, v[136:137]
	v_mov_b32_e32 v139, v117
	global_load_dwordx4 v[8:11], v[8:9], off
	v_lshl_add_u64 v[12:13], v[28:29], 0, v[138:139]
	v_mov_b32_e32 v141, v117
	global_load_dwordx4 v[12:15], v[12:13], off
	v_lshl_add_u64 v[16:17], v[24:25], 0, v[140:141]
	v_mov_b32_e32 v143, v117
	global_load_dwordx4 v[16:19], v[16:17], off
	v_lshl_add_u64 v[20:21], v[28:29], 0, v[142:143]
	v_mov_b32_e32 v149, v117
	global_load_dwordx4 v[20:23], v[20:21], off
	v_lshl_add_u64 v[24:25], v[24:25], 0, v[148:149]
	v_mov_b32_e32 v151, v117
	global_load_dwordx4 v[24:27], v[24:25], off
	v_lshl_add_u64 v[28:29], v[28:29], 0, v[150:151]
	global_load_dwordx4 v[28:31], v[28:29], off
	s_add_i32 s18, s34, s33
	s_ashr_i32 s19, s18, 31
	s_lshl_b64 s[16:17], s[18:19], 2
	s_add_u32 s16, s46, s16
	s_addc_u32 s17, s47, s17
	s_lshl_b64 s[18:19], s[18:19], 13
	s_add_u32 s18, s48, s18
	s_addc_u32 s19, s49, s19
	v_lshlrev_b32_e32 v232, 1, v175
	v_lshlrev_b32_e32 v233, 1, v176
	global_load_ushort v230, v232, s[18:19]
	global_load_ushort v231, v233, s[18:19]
	s_waitcnt vmcnt(9)
	ds_write_b128 v115, v[0:3]
	s_waitcnt vmcnt(8)
	ds_write_b128 v168, v[4:7]
	s_waitcnt vmcnt(7)
	ds_write_b128 v169, v[8:11]
	s_waitcnt vmcnt(6)
	ds_write_b128 v170, v[12:15]
	s_waitcnt vmcnt(5)
	ds_write_b128 v171, v[16:19]
	s_waitcnt vmcnt(4)
	ds_write_b128 v172, v[20:23]
	s_waitcnt vmcnt(3)
	ds_write_b128 v173, v[24:27]
	s_waitcnt vmcnt(2)
	ds_write_b128 v174, v[28:31]
	s_waitcnt lgkmcnt(0)
	s_waitcnt vmcnt(1)
	v_and_b32_e32 v137, 0xfff, v230
	v_lshlrev_b32_e32 v232, 7, v137
	v_mov_b32_e32 v233, 0
	v_lshl_add_u64 v[4:5], v[156:157], 0, v[232:233]
	global_load_dwordx4 v[0:3], v[4:5], off
	s_nop 0
	global_load_dwordx4 v[4:7], v[4:5], off offset:64
	s_waitcnt vmcnt(2)
	v_and_b32_e32 v139, 0xfff, v231
	v_lshlrev_b32_e32 v232, 7, v139
	v_lshl_add_u64 v[12:13], v[156:157], 0, v[232:233]
	global_load_dwordx4 v[8:11], v[12:13], off
	s_nop 0
	global_load_dwordx4 v[12:15], v[12:13], off offset:64
	s_barrier
	global_load_dword v133, v117, s[16:17]
	s_waitcnt vmcnt(0)
	v_add_u32_e32 v232, 31, v133
	v_ashrrev_i32_e32 v135, 5, v232
	v_cmp_lt_i32_e32 vcc, v196, v135
	s_and_saveexec_b64 s[16:17], vcc
	s_cbranch_execz .LBB0_252
	v_cmp_lt_i32_e64 s[20:21], v175, v133
	v_cmp_lt_i32_e64 s[24:25], v176, v133
	s_mov_b64 s[22:23], 0
	v_mov_b32_e32 v143, v196
	v_mov_b32_e32 v141, v230
	v_mov_b32_e32 v149, v231
	s_branch .LBB0_258

.LBB0_258:
	v_mov_b32_e32 v16, v143
	v_add_u32_e32 v143, 8, v16
	v_cmp_lt_i32_e32 vcc, v143, v135
	s_mov_b64 s[28:29], s[20:21]
	v_mov_b32_e32 v161, v141
	v_cndmask_b32_e32 v16, v16, v143, vcc
	v_lshl_or_b32 v18, v16, 5, v146
	v_cmp_lt_i32_e64 s[20:21], v18, v133
	s_mov_b64 s[26:27], s[24:25]
	v_mov_b32_e32 v151, v149
	v_cndmask_b32_e64 v16, 0, v18, s[20:21]
	v_ashrrev_i32_e32 v17, 31, v16
	v_lshl_add_u64 v[16:17], v[16:17], 1, s[18:19]
	global_load_ushort v141, v[16:17], off
	v_or_b32_e32 v16, 16, v18
	v_cmp_lt_i32_e64 s[24:25], v16, v133
	v_mov_b32_e32 v162, v137
	v_mov_b32_e32 v160, v139
	v_cndmask_b32_e64 v16, 0, v16, s[24:25]
	v_ashrrev_i32_e32 v17, 31, v16
	v_lshl_add_u64 v[16:17], v[16:17], 1, s[18:19]
	global_load_ushort v149, v[16:17], off
	s_waitcnt vmcnt(14)
	v_mov_b64_e32 v[46:47], v[6:7]
	s_waitcnt vmcnt(12)
	v_mov_b64_e32 v[34:35], v[14:15]
	v_mov_b64_e32 v[44:45], v[4:5]
	v_mov_b64_e32 v[32:33], v[12:13]
	v_mov_b64_e32 v[38:39], v[10:11]
	v_mov_b64_e32 v[42:43], v[2:3]
	v_mov_b64_e32 v[36:37], v[8:9]
	v_mov_b64_e32 v[40:41], v[0:1]
	v_cmp_ge_i32_e32 vcc, v143, v135
	v_mov_b32_e32 v158, 0
	s_mov_b32 s0, 0
	s_or_b64 s[22:23], vcc, s[22:23]
	v_mov_b32_e32 v166, 0xf149f2ca
	v_mov_b32_e32 v159, v158
	v_mov_b32_e32 v164, 0xf149f2ca
	v_mov_b32_e32 v60, v158
	v_mov_b32_e32 v61, v158
	v_mov_b32_e32 v62, v158
	v_mov_b32_e32 v63, v158
	v_mov_b32_e32 v56, v158
	v_mov_b32_e32 v57, v158
	v_mov_b32_e32 v58, v158
	v_mov_b32_e32 v59, v158
	v_mov_b32_e32 v52, v158
	v_mov_b32_e32 v53, v158
	v_mov_b32_e32 v54, v158
	v_mov_b32_e32 v55, v158
	v_mov_b32_e32 v48, v158
	v_mov_b32_e32 v49, v158
	v_mov_b32_e32 v50, v158
	v_mov_b32_e32 v51, v158
	v_mov_b32_e32 v28, v158
	v_mov_b32_e32 v29, v158
	v_mov_b32_e32 v30, v158
	v_mov_b32_e32 v31, v158
	v_mov_b32_e32 v24, v158
	v_mov_b32_e32 v25, v158
	v_mov_b32_e32 v26, v158
	v_mov_b32_e32 v27, v158
	v_mov_b32_e32 v20, v158
	v_mov_b32_e32 v21, v158
	v_mov_b32_e32 v22, v158
	v_mov_b32_e32 v23, v158
	v_mov_b32_e32 v16, v158
	v_mov_b32_e32 v17, v158
	v_mov_b32_e32 v18, v158
	v_mov_b32_e32 v19, v158
	v_mov_b32_e32 v116, v125
.LBB0_259:
	ds_read_b128 v[64:67], v116
	ds_read_b128 v[72:75], v116 offset:64
	ds_read_b128 v[76:79], v116 offset:2304
	ds_read_b128 v[100:103], v116 offset:2368
	v_mov_b32_e32 v163, v164
	v_add_u32_e32 v164, s0, v121
	s_waitcnt lgkmcnt(1)
	v_mfma_f32_16x16x32_bf16 v[198:201], v[76:79], v[40:43], 0
	v_mov_b32_e32 v165, v166
	v_add_u32_e32 v166, 0x2000, v164
	v_add_u32_e32 v167, 0x4000, v164
	v_mfma_f32_16x16x32_bf16 v[104:107], v[76:79], v[36:39], 0
	ds_read_b128 v[80:83], v116 offset:4608
	ds_read_b128 v[76:79], v116 offset:4672
	s_addk_i32 s0, 0x80
	s_cmpk_eq_i32 s0, 0x200
	v_mfma_f32_16x16x32_bf16 v[68:71], v[64:67], v[40:43], 0
	v_mfma_f32_16x16x32_bf16 v[64:67], v[64:67], v[36:39], 0
	s_waitcnt lgkmcnt(1)
	v_mfma_f32_16x16x32_bf16 v[92:95], v[80:83], v[40:43], 0
	v_mfma_f32_16x16x32_bf16 v[84:87], v[80:83], v[36:39], 0
	ds_read_b128 v[88:91], v116 offset:6912
	ds_read_b128 v[80:83], v116 offset:6976
	v_add_u32_e32 v116, 0x2400, v116
	s_waitcnt lgkmcnt(1)
	v_mfma_f32_16x16x32_bf16 v[96:99], v[88:91], v[40:43], 0
	v_mfma_f32_16x16x32_bf16 v[88:91], v[88:91], v[36:39], 0
	v_mfma_f32_16x16x32_bf16 v[68:71], v[72:75], v[44:47], v[68:71]
	v_mfma_f32_16x16x32_bf16 v[72:75], v[72:75], v[32:35], v[64:67]
	v_mfma_f32_16x16x32_bf16 v[64:67], v[100:103], v[44:47], v[198:201]
	v_mfma_f32_16x16x32_bf16 v[100:103], v[100:103], v[32:35], v[104:107]
	s_nop 2
	ds_read2_b64 v[104:107], v164 offset1:4
	ds_read2_b64 v[198:201], v164 offset0:8 offset1:12
	v_add_u32_e32 v164, 0x6000, v164
	v_mfma_f32_16x16x32_bf16 v[92:95], v[76:79], v[44:47], v[92:95]
	v_mfma_f32_16x16x32_bf16 v[76:79], v[76:79], v[32:35], v[84:87]
	s_nop 2
	ds_read2_b64 v[84:87], v166 offset0:32 offset1:36
	ds_read2_b64 v[202:205], v166 offset0:40 offset1:44
	ds_read2_b64 v[206:209], v167 offset0:64 offset1:68
	ds_read2_b64 v[210:213], v167 offset0:72 offset1:76
	ds_read2_b64 v[214:217], v164 offset0:96 offset1:100
	ds_read2_b64 v[218:221], v164 offset0:104 offset1:108
	s_waitcnt lgkmcnt(8)
	v_mfma_f32_16x16x32_bf16 v[96:99], v[80:83], v[44:47], v[96:99]
	v_mfma_f32_16x16x32_bf16 v[80:83], v[80:83], v[32:35], v[88:91]
	s_nop 2
	v_max3_f32 v88, v68, s4, v69
	v_max3_f32 v89, v72, s4, v73
	v_max3_f32 v88, v88, v70, v71
	v_max3_f32 v89, v89, v74, v75
	v_max3_f32 v88, v88, v64, v65
	v_max3_f32 v89, v89, v100, v101
	v_max3_f32 v88, v88, v66, v67
	v_max3_f32 v89, v89, v102, v103
	v_max3_f32 v88, v88, v92, v93
	v_max3_f32 v89, v89, v76, v77
	v_max3_f32 v88, v88, v94, v95
	v_max3_f32 v89, v89, v78, v79
	v_max3_f32 v88, v88, v96, v97
	v_max3_f32 v89, v89, v80, v81
	v_max3_f32 v88, v88, v98, v99
	v_max3_f32 v89, v89, v82, v83
	v_mov_b32_e32 v90, v88
	v_mov_b32_e32 v91, v89
	s_nop 0
	v_permlane16_swap_b32_e32 v90, v88
	v_permlane16_swap_b32_e32 v91, v89
	v_max_f32_e32 v88, v88, v90
	v_max_f32_e32 v89, v89, v91
	v_mov_b32_e32 v90, v88
	v_mov_b32_e32 v91, v89
	s_nop 0
	v_permlane32_swap_b32_e32 v90, v88
	v_permlane32_swap_b32_e32 v91, v89
	v_max3_f32 v164, v163, v89, v91
	v_max3_f32 v166, v165, v88, v90
	v_sub_f32_e32 v89, v163, v164
	v_sub_f32_e32 v88, v165, v166
	v_sub_f32_e32 v68, v68, v166
	v_sub_f32_e32 v90, v72, v164
	v_sub_f32_e32 v69, v69, v166
	v_sub_f32_e32 v91, v73, v164
	v_sub_f32_e32 v70, v70, v166
	v_sub_f32_e32 v163, v74, v164
	v_sub_f32_e32 v71, v71, v166
	v_sub_f32_e32 v165, v75, v164
	v_sub_f32_e32 v64, v64, v166
	v_sub_f32_e32 v100, v100, v164
	v_sub_f32_e32 v65, v65, v166
	v_sub_f32_e32 v101, v101, v164
	v_sub_f32_e32 v66, v66, v166
	v_sub_f32_e32 v102, v102, v164
	v_sub_f32_e32 v67, v67, v166
	v_sub_f32_e32 v103, v103, v164
	v_exp_f32_e32 v73, v89
	v_sub_f32_e32 v167, v92, v166
	v_sub_f32_e32 v179, v76, v164
	v_sub_f32_e32 v178, v93, v166
	v_sub_f32_e32 v185, v77, v164
	v_sub_f32_e32 v187, v78, v164
	v_sub_f32_e32 v222, v79, v164
	v_sub_f32_e32 v224, v80, v164
	v_sub_f32_e32 v225, v81, v164
	v_sub_f32_e32 v227, v82, v164
	v_sub_f32_e32 v228, v83, v164
	v_exp_f32_e32 v72, v88
	v_exp_f32_e32 v74, v68
	v_exp_f32_e32 v75, v90
	v_exp_f32_e32 v76, v69
	v_exp_f32_e32 v77, v91
	v_exp_f32_e32 v78, v70
	v_exp_f32_e32 v79, v163
	v_exp_f32_e32 v80, v71
	v_exp_f32_e32 v81, v165
	v_exp_f32_e32 v82, v64
	v_exp_f32_e32 v83, v100
	v_exp_f32_e32 v88, v65
	v_exp_f32_e32 v89, v101
	v_exp_f32_e32 v90, v66
	v_exp_f32_e32 v91, v102
	v_exp_f32_e32 v92, v67
	v_exp_f32_e32 v93, v103
	v_sub_f32_e32 v186, v94, v166
	v_sub_f32_e32 v226, v98, v166
	v_exp_f32_e32 v98, v186
	v_mov_b32_e32 v186, v73
	v_sub_f32_e32 v95, v95, v166
	v_sub_f32_e32 v223, v96, v166
	v_sub_f32_e32 v97, v97, v166
	v_sub_f32_e32 v99, v99, v166
	v_pk_mul_f32 v[62:63], v[62:63], v[72:73] op_sel_hi:[1,0]
	v_pk_mul_f32 v[60:61], v[60:61], v[72:73] op_sel_hi:[1,0]
	v_pk_mul_f32 v[58:59], v[58:59], v[72:73] op_sel_hi:[1,0]
	v_cvt_pk_bf16_f32 v64, v74, v76
	v_cvt_pk_bf16_f32 v65, v78, v80
	v_cvt_pk_bf16_f32 v66, v82, v88
	v_cvt_pk_bf16_f32 v67, v90, v92
	v_pk_mul_f32 v[56:57], v[56:57], v[72:73] op_sel_hi:[1,0]
	v_cvt_pk_bf16_f32 v68, v75, v77
	v_cvt_pk_bf16_f32 v69, v79, v81
	v_cvt_pk_bf16_f32 v70, v83, v89
	v_cvt_pk_bf16_f32 v71, v91, v93
	v_pk_mul_f32 v[30:31], v[30:31], v[186:187] op_sel_hi:[1,0]
	v_pk_mul_f32 v[28:29], v[28:29], v[186:187] op_sel_hi:[1,0]
	v_pk_mul_f32 v[26:27], v[26:27], v[186:187] op_sel_hi:[1,0]
	v_pk_mul_f32 v[24:25], v[24:25], v[186:187] op_sel_hi:[1,0]
	v_exp_f32_e32 v94, v167
	v_exp_f32_e32 v96, v178
	v_exp_f32_e32 v100, v95
	v_exp_f32_e32 v102, v223
	v_exp_f32_e32 v178, v97
	s_waitcnt lgkmcnt(7)
	v_mfma_f32_16x16x32_bf16 v[60:63], v[104:107], v[64:67], v[60:63]
	v_mul_f32_e64 v54, v54, v72
	v_mul_f32_e64 v55, v55, v72
	v_pk_mul_f32 v[52:53], v[52:53], v[72:73] op_sel_hi:[1,0]
	v_pk_mul_f32 v[50:51], v[50:51], v[72:73] op_sel_hi:[1,0]
	s_waitcnt lgkmcnt(5)
	v_mfma_f32_16x16x32_bf16 v[56:59], v[84:87], v[64:67], v[56:59]
	v_mul_f32_e64 v48, v48, v72
	v_mul_f32_e64 v49, v49, v72
	v_exp_f32_e32 v95, v179
	v_exp_f32_e32 v97, v185
	v_mfma_f32_16x16x32_bf16 v[28:31], v[104:107], v[68:71], v[28:31]
	v_exp_f32_e32 v104, v226
	v_exp_f32_e32 v101, v222
	v_exp_f32_e32 v103, v224
	v_mfma_f32_16x16x32_bf16 v[24:27], v[84:87], v[68:71], v[24:27]
	v_exp_f32_e32 v84, v99
	v_exp_f32_e32 v99, v187
	v_exp_f32_e32 v179, v225
	s_waitcnt lgkmcnt(3)
	v_mfma_f32_16x16x32_bf16 v[52:55], v[206:209], v[64:67], v[52:55]
	v_exp_f32_e32 v105, v227
	v_pk_mul_f32 v[22:23], v[22:23], v[186:187] op_sel_hi:[1,0]
	v_pk_mul_f32 v[20:21], v[20:21], v[186:187] op_sel_hi:[1,0]
	s_waitcnt lgkmcnt(1)
	v_mfma_f32_16x16x32_bf16 v[48:51], v[214:217], v[64:67], v[48:51]
	v_cvt_pk_bf16_f32 v64, v94, v96
	v_cvt_pk_bf16_f32 v65, v98, v100
	v_cvt_pk_bf16_f32 v66, v102, v178
	v_cvt_pk_bf16_f32 v67, v104, v84
	v_pk_mul_f32 v[18:19], v[18:19], v[186:187] op_sel_hi:[1,0]
	v_pk_mul_f32 v[16:17], v[16:17], v[186:187] op_sel_hi:[1,0]
	v_mfma_f32_16x16x32_bf16 v[60:63], v[198:201], v[64:67], v[60:63]
	v_exp_f32_e32 v85, v228
	v_mfma_f32_16x16x32_bf16 v[56:59], v[202:205], v[64:67], v[56:59]
	v_mfma_f32_16x16x32_bf16 v[52:55], v[210:213], v[64:67], v[52:55]
	s_waitcnt lgkmcnt(0)
	v_mfma_f32_16x16x32_bf16 v[48:51], v[218:221], v[64:67], v[48:51]
	v_add_f32_e64 v64, v74, 0
	v_add_f32_e64 v65, v75, 0
	v_pk_add_f32 v[64:65], v[76:77], v[64:65]
	v_mfma_f32_16x16x32_bf16 v[20:23], v[206:209], v[68:71], v[20:23]
	v_add_f32_e64 v64, v78, v64
	v_add_f32_e64 v65, v79, v65
	v_pk_add_f32 v[64:65], v[80:81], v[64:65]
	v_mfma_f32_16x16x32_bf16 v[16:19], v[214:217], v[68:71], v[16:19]
	v_add_f32_e64 v64, v82, v64
	v_add_f32_e64 v65, v83, v65
	v_cvt_pk_bf16_f32 v68, v95, v97
	v_pk_add_f32 v[64:65], v[88:89], v[64:65]
	v_cvt_pk_bf16_f32 v69, v99, v101
	v_pk_add_f32 v[64:65], v[90:91], v[64:65]
	v_cvt_pk_bf16_f32 v70, v103, v179
	v_pk_add_f32 v[64:65], v[92:93], v[64:65]
	v_cvt_pk_bf16_f32 v71, v105, v85
	v_pk_add_f32 v[64:65], v[94:95], v[64:65]
	s_nop 0
	v_pk_add_f32 v[64:65], v[96:97], v[64:65]
	v_mfma_f32_16x16x32_bf16 v[28:31], v[198:201], v[68:71], v[28:31]
	v_add_f32_e64 v64, v98, v64
	v_add_f32_e64 v65, v99, v65
	v_pk_add_f32 v[64:65], v[100:101], v[64:65]
	v_mfma_f32_16x16x32_bf16 v[24:27], v[202:205], v[68:71], v[24:27]
	v_add_f32_e64 v64, v102, v64
	v_add_f32_e64 v65, v103, v65
	v_pk_add_f32 v[64:65], v[178:179], v[64:65]
	v_mfma_f32_16x16x32_bf16 v[20:23], v[210:213], v[68:71], v[20:23]
	v_add_f32_e64 v64, v104, v64
	v_add_f32_e64 v65, v105, v65
	v_pk_add_f32 v[64:65], v[84:85], v[64:65]
	v_mfma_f32_16x16x32_bf16 v[16:19], v[218:221], v[68:71], v[16:19]
	v_mov_b32_e32 v66, v64
	v_mov_b32_e32 v67, v65
	s_nop 0
	v_permlane16_swap_b32_e32 v66, v64
	v_permlane16_swap_b32_e32 v67, v65
	v_pk_add_f32 v[64:65], v[64:65], v[66:67]
	s_nop 0
	v_mov_b32_e32 v66, v64
	v_mov_b32_e32 v67, v65
	s_nop 0
	v_permlane32_swap_b32_e32 v66, v64
	v_permlane32_swap_b32_e32 v67, v65
	v_pk_add_f32 v[64:65], v[64:65], v[66:67]
	s_nop 0
	v_pk_fma_f32 v[158:159], v[158:159], v[72:73], v[64:65]
	s_cmpk_lg_i32 s0, 0x80
	s_cbranch_scc1 .Lpast_qskip
	s_cmp_lg_u64 s[22:23], 0
	s_cbranch_scc1 .Lpast_qskip
	v_mov_b32_e32 v233, 0
	s_waitcnt vmcnt(1)
	v_and_b32_e32 v137, 0xfff, v141
	v_lshlrev_b32_e32 v232, 7, v137
	v_lshl_add_u64 v[4:5], v[156:157], 0, v[232:233]
	global_load_dwordx4 v[0:3], v[4:5], off
	s_nop 0
	global_load_dwordx4 v[4:7], v[4:5], off offset:64
	s_waitcnt vmcnt(2)
	v_and_b32_e32 v139, 0xfff, v149
	v_lshlrev_b32_e32 v232, 7, v139
	v_lshl_add_u64 v[12:13], v[156:157], 0, v[232:233]
	global_load_dwordx4 v[8:11], v[12:13], off
	s_nop 0
	global_load_dwordx4 v[12:15], v[12:13], off offset:64
